# attention steady loop: B2 V-fragment LDS reads prefetched in B1 gaps, K(t+1) fragment loads moved into B2 (hides LDS latency)
# baseline (speedup 1.0000x reference)
.LBB0_843:
	s_setprio 1
	s_waitcnt lgkmcnt(14)
	v_mfma_f32_32x32x16_bf16 v[0:15], v[140:143], v[196:199], v[0:15]
	v_exp_f32_e32 v80, v96
	v_exp_f32_e32 v81, v97
	v_exp_f32_e32 v82, v98
	v_exp_f32_e32 v83, v99
	v_exp_f32_e32 v64, v112
	v_exp_f32_e32 v65, v113
	s_waitcnt lgkmcnt(12)
	v_mfma_f32_32x32x16_bf16 v[48:63], v[140:143], v[188:191], v[48:63]
	v_exp_f32_e32 v66, v114
	v_exp_f32_e32 v67, v115
	v_exp_f32_e32 v84, v100
	v_exp_f32_e32 v85, v101
	v_exp_f32_e32 v86, v102
	v_exp_f32_e32 v87, v103
	ds_read_b64_tr_b16 v[100:101], v200 offset:32768
	ds_read_b64_tr_b16 v[102:103], v200 offset:33280
	s_waitcnt lgkmcnt(12)
	v_mfma_f32_32x32x16_bf16 v[0:15], v[136:139], v[184:187], v[0:15]
	v_exp_f32_e32 v88, v104
	v_exp_f32_e32 v89, v105
	v_exp_f32_e32 v90, v106
	v_exp_f32_e32 v91, v107
	ds_read_b64_tr_b16 v[104:105], v200 offset:33792
	ds_read_b64_tr_b16 v[106:107], v200 offset:34304
	s_waitcnt lgkmcnt(12)
	v_mfma_f32_32x32x16_bf16 v[48:63], v[136:139], v[180:183], v[48:63]
	v_exp_f32_e32 v92, v108
	v_exp_f32_e32 v93, v109
	v_exp_f32_e32 v94, v110
	v_exp_f32_e32 v95, v111
	ds_read_b64_tr_b16 v[108:109], v200 offset:36864
	ds_read_b64_tr_b16 v[110:111], v200 offset:37376
	s_waitcnt lgkmcnt(12)
	v_mfma_f32_32x32x16_bf16 v[0:15], v[132:135], v[192:195], v[0:15]
	v_exp_f32_e32 v68, v116
	v_exp_f32_e32 v69, v117
	v_exp_f32_e32 v70, v118
	v_exp_f32_e32 v71, v119
	ds_read_b64_tr_b16 v[116:117], v200 offset:37888
	ds_read_b64_tr_b16 v[118:119], v200 offset:38400
	s_waitcnt lgkmcnt(12)
	v_mfma_f32_32x32x16_bf16 v[48:63], v[132:135], v[172:175], v[48:63]
	v_exp_f32_e32 v72, v120
	v_exp_f32_e32 v73, v121
	v_exp_f32_e32 v74, v122
	v_exp_f32_e32 v75, v123
	s_waitcnt lgkmcnt(10)
	v_mfma_f32_32x32x16_bf16 v[0:15], v[128:131], v[168:171], v[0:15]
	v_exp_f32_e32 v76, v124
	v_exp_f32_e32 v77, v125
	v_exp_f32_e32 v78, v126
	v_exp_f32_e32 v79, v127
	s_waitcnt lgkmcnt(8)
	v_mfma_f32_32x32x16_bf16 v[48:63], v[128:131], v[176:179], v[48:63]
	v_add_u32_e32 v120, s22, v214
	s_waitcnt lgkmcnt(6)
	v_mfma_f32_32x32x16_bf16 v[32:47], v[140:143], v[100:103], v[32:47]
	ds_read_b128 v[96:99], v120
	ds_read_b128 v[112:115], v120 offset:512
	s_waitcnt lgkmcnt(4)
	v_mfma_f32_32x32x16_bf16 v[16:31], v[140:143], v[108:111], v[16:31]
	ds_read_b64_tr_b16 v[100:101], v200 offset:34816
	ds_read_b64_tr_b16 v[102:103], v200 offset:35328
	ds_read_b64_tr_b16 v[108:109], v200 offset:38912
	ds_read_b64_tr_b16 v[110:111], v200 offset:39424
	v_mfma_f32_32x32x16_bf16 v[32:47], v[136:139], v[104:107], v[32:47]
	s_waitcnt lgkmcnt(6)
	v_mfma_f32_32x32x16_bf16 v[16:31], v[136:139], v[116:119], v[16:31]
	ds_read_b64_tr_b16 v[104:105], v200 offset:35840
	ds_read_b64_tr_b16 v[106:107], v200 offset:36352
	ds_read_b64_tr_b16 v[116:117], v200 offset:39936
	ds_read_b64_tr_b16 v[118:119], v200 offset:40448
	ds_read_b128 v[196:199], v120 offset:2048
	ds_read_b128 v[188:191], v120 offset:2560
	s_waitcnt lgkmcnt(8)
	v_mfma_f32_32x32x16_bf16 v[32:47], v[132:135], v[100:103], v[32:47]
	s_waitcnt lgkmcnt(6)
	v_mfma_f32_32x32x16_bf16 v[16:31], v[132:135], v[108:111], v[16:31]
	ds_read_b128 v[184:187], v120 offset:4096
	ds_read_b128 v[164:167], v120 offset:4608
	s_waitcnt lgkmcnt(6)
	v_mfma_f32_32x32x16_bf16 v[32:47], v[128:131], v[104:107], v[32:47]
	ds_read_b128 v[180:183], v120 offset:6144
	ds_read_b128 v[160:163], v120 offset:6656
	s_waitcnt lgkmcnt(6)
	v_mfma_f32_32x32x16_bf16 v[16:31], v[128:131], v[116:119], v[16:31]
	s_setprio 0
	s_waitcnt vmcnt(3) lgkmcnt(0)
	s_barrier
	s_andn2_b64 vcc, exec, s[0:1]
	s_cbranch_vccnz .LBB0_845
	s_waitcnt lgkmcnt(0)
	v_add_u32_e32 v116, s37, v221
	ds_read_b128 v[100:103], v116 offset:96
	ds_read_b128 v[104:107], v116 offset:64
	ds_read_b128 v[108:111], v116 offset:32
	ds_read_b128 v[116:119], v116
	s_waitcnt lgkmcnt(3)
	v_pk_mul_f32 v[12:13], v[12:13], v[100:101]
	s_waitcnt lgkmcnt(2)
	v_pk_mul_f32 v[8:9], v[8:9], v[104:105]
	s_waitcnt lgkmcnt(1)
	v_pk_mul_f32 v[4:5], v[4:5], v[108:109]
	v_pk_mul_f32 v[14:15], v[14:15], v[102:103]
	v_pk_mul_f32 v[10:11], v[10:11], v[106:107]
	v_pk_mul_f32 v[6:7], v[6:7], v[110:111]
	s_waitcnt lgkmcnt(0)
	v_pk_mul_f32 v[2:3], v[2:3], v[118:119]
	v_pk_mul_f32 v[0:1], v[0:1], v[116:117]
	v_pk_mul_f32 v[60:61], v[60:61], v[100:101]
	v_pk_mul_f32 v[56:57], v[56:57], v[104:105]
	v_pk_mul_f32 v[52:53], v[52:53], v[108:109]
	v_pk_mul_f32 v[62:63], v[62:63], v[102:103]
	v_pk_mul_f32 v[58:59], v[58:59], v[106:107]
	v_pk_mul_f32 v[54:55], v[54:55], v[110:111]
	v_pk_mul_f32 v[50:51], v[50:51], v[118:119]
	v_pk_mul_f32 v[48:49], v[48:49], v[116:117]
	v_pk_mul_f32 v[44:45], v[44:45], v[100:101]
	v_pk_mul_f32 v[40:41], v[40:41], v[104:105]
	v_pk_mul_f32 v[36:37], v[36:37], v[108:109]
	v_pk_mul_f32 v[46:47], v[46:47], v[102:103]
	v_pk_mul_f32 v[42:43], v[42:43], v[106:107]
	v_pk_mul_f32 v[38:39], v[38:39], v[110:111]
	v_pk_mul_f32 v[34:35], v[34:35], v[118:119]
	v_pk_mul_f32 v[32:33], v[32:33], v[116:117]
	v_pk_mul_f32 v[28:29], v[28:29], v[100:101]
	v_pk_mul_f32 v[24:25], v[24:25], v[104:105]
	v_pk_mul_f32 v[20:21], v[20:21], v[108:109]
	v_pk_mul_f32 v[30:31], v[30:31], v[102:103]
	v_pk_mul_f32 v[26:27], v[26:27], v[106:107]
	v_pk_mul_f32 v[22:23], v[22:23], v[110:111]
	v_pk_mul_f32 v[18:19], v[18:19], v[118:119]
	v_pk_mul_f32 v[16:17], v[16:17], v[116:117]

.LBB0_846:
	s_setprio 1
	s_waitcnt lgkmcnt(14)
	v_mfma_f32_32x32x16_bf16 v[0:15], v[140:143], v[200:203], v[0:15]
	v_exp_f32_e32 v80, v96
	v_exp_f32_e32 v81, v97
	v_exp_f32_e32 v82, v98
	v_exp_f32_e32 v83, v99
	v_exp_f32_e32 v64, v112
	v_exp_f32_e32 v65, v113
	s_waitcnt lgkmcnt(12)
	v_mfma_f32_32x32x16_bf16 v[48:63], v[140:143], v[176:179], v[48:63]
	v_exp_f32_e32 v66, v114
	v_exp_f32_e32 v67, v115
	v_exp_f32_e32 v84, v100
	v_exp_f32_e32 v85, v101
	v_exp_f32_e32 v86, v102
	v_exp_f32_e32 v87, v103
	ds_read_b64_tr_b16 v[100:101], v255 offset:32768
	ds_read_b64_tr_b16 v[102:103], v255 offset:33280
	s_waitcnt lgkmcnt(12)
	v_mfma_f32_32x32x16_bf16 v[0:15], v[136:139], v[168:171], v[0:15]
	v_exp_f32_e32 v88, v104
	v_exp_f32_e32 v89, v105
	v_exp_f32_e32 v90, v106
	v_exp_f32_e32 v91, v107
	ds_read_b64_tr_b16 v[104:105], v255 offset:33792
	ds_read_b64_tr_b16 v[106:107], v255 offset:34304
	s_waitcnt lgkmcnt(12)
	v_mfma_f32_32x32x16_bf16 v[48:63], v[136:139], v[172:175], v[48:63]
	v_exp_f32_e32 v92, v108
	v_exp_f32_e32 v93, v109
	v_exp_f32_e32 v94, v110
	v_exp_f32_e32 v95, v111
	ds_read_b64_tr_b16 v[108:109], v255 offset:36864
	ds_read_b64_tr_b16 v[110:111], v255 offset:37376
	s_waitcnt lgkmcnt(12)
	v_mfma_f32_32x32x16_bf16 v[0:15], v[132:135], v[196:199], v[0:15]
	v_exp_f32_e32 v68, v116
	v_exp_f32_e32 v69, v117
	v_exp_f32_e32 v70, v118
	v_exp_f32_e32 v71, v119
	ds_read_b64_tr_b16 v[116:117], v255 offset:37888
	ds_read_b64_tr_b16 v[118:119], v255 offset:38400
	s_waitcnt lgkmcnt(12)
	v_mfma_f32_32x32x16_bf16 v[48:63], v[132:135], v[184:187], v[48:63]
	v_exp_f32_e32 v72, v120
	v_exp_f32_e32 v73, v121
	v_exp_f32_e32 v74, v122
	v_exp_f32_e32 v75, v123
	s_waitcnt lgkmcnt(10)
	v_mfma_f32_32x32x16_bf16 v[0:15], v[128:131], v[188:191], v[0:15]
	v_exp_f32_e32 v76, v124
	v_exp_f32_e32 v77, v125
	v_exp_f32_e32 v78, v126
	v_exp_f32_e32 v79, v127
	s_waitcnt lgkmcnt(8)
	v_mfma_f32_32x32x16_bf16 v[48:63], v[128:131], v[192:195], v[48:63]
	v_add_u32_e32 v120, s24, v214
	s_waitcnt lgkmcnt(6)
	v_mfma_f32_32x32x16_bf16 v[32:47], v[140:143], v[100:103], v[32:47]
	ds_read_b128 v[96:99], v120
	ds_read_b128 v[112:115], v120 offset:512
	s_waitcnt lgkmcnt(4)
	v_mfma_f32_32x32x16_bf16 v[16:31], v[140:143], v[108:111], v[16:31]
	ds_read_b64_tr_b16 v[100:101], v255 offset:34816
	ds_read_b64_tr_b16 v[102:103], v255 offset:35328
	ds_read_b64_tr_b16 v[108:109], v255 offset:38912
	ds_read_b64_tr_b16 v[110:111], v255 offset:39424
	v_mfma_f32_32x32x16_bf16 v[32:47], v[136:139], v[104:107], v[32:47]
	s_waitcnt lgkmcnt(6)
	v_mfma_f32_32x32x16_bf16 v[16:31], v[136:139], v[116:119], v[16:31]
	ds_read_b64_tr_b16 v[104:105], v255 offset:35840
	ds_read_b64_tr_b16 v[106:107], v255 offset:36352
	ds_read_b64_tr_b16 v[116:117], v255 offset:39936
	ds_read_b64_tr_b16 v[118:119], v255 offset:40448
	ds_read_b128 v[180:183], v120 offset:2048
	ds_read_b128 v[176:179], v120 offset:2560
	s_waitcnt lgkmcnt(8)
	v_mfma_f32_32x32x16_bf16 v[32:47], v[132:135], v[100:103], v[32:47]
	s_waitcnt lgkmcnt(6)
	v_mfma_f32_32x32x16_bf16 v[16:31], v[132:135], v[108:111], v[16:31]
	ds_read_b128 v[172:175], v120 offset:4096
	ds_read_b128 v[168:171], v120 offset:4608
	s_waitcnt lgkmcnt(6)
	v_mfma_f32_32x32x16_bf16 v[32:47], v[128:131], v[104:107], v[32:47]
	ds_read_b128 v[164:167], v120 offset:6144
	ds_read_b128 v[160:163], v120 offset:6656
	s_waitcnt lgkmcnt(6)
	v_mfma_f32_32x32x16_bf16 v[16:31], v[128:131], v[116:119], v[16:31]
	s_setprio 0
	s_waitcnt vmcnt(3) lgkmcnt(0)
	s_barrier
	s_andn2_b64 vcc, exec, s[0:1]
	s_cbranch_vccnz .LBB0_848
	s_waitcnt lgkmcnt(0)
	v_add_u32_e32 v116, s37, v221
	ds_read_b128 v[100:103], v116 offset:96
	ds_read_b128 v[104:107], v116 offset:64
	ds_read_b128 v[108:111], v116 offset:32
	ds_read_b128 v[116:119], v116
	s_waitcnt lgkmcnt(3)
	v_pk_mul_f32 v[12:13], v[12:13], v[100:101]
	s_waitcnt lgkmcnt(2)
	v_pk_mul_f32 v[8:9], v[8:9], v[104:105]
	s_waitcnt lgkmcnt(1)
	v_pk_mul_f32 v[4:5], v[4:5], v[108:109]
	v_pk_mul_f32 v[14:15], v[14:15], v[102:103]
	v_pk_mul_f32 v[10:11], v[10:11], v[106:107]
	v_pk_mul_f32 v[6:7], v[6:7], v[110:111]
	s_waitcnt lgkmcnt(0)
	v_pk_mul_f32 v[2:3], v[2:3], v[118:119]
	v_pk_mul_f32 v[0:1], v[0:1], v[116:117]
	v_pk_mul_f32 v[60:61], v[60:61], v[100:101]
	v_pk_mul_f32 v[56:57], v[56:57], v[104:105]
	v_pk_mul_f32 v[52:53], v[52:53], v[108:109]
	v_pk_mul_f32 v[62:63], v[62:63], v[102:103]
	v_pk_mul_f32 v[58:59], v[58:59], v[106:107]
	v_pk_mul_f32 v[54:55], v[54:55], v[110:111]
	v_pk_mul_f32 v[50:51], v[50:51], v[118:119]
	v_pk_mul_f32 v[48:49], v[48:49], v[116:117]
	v_pk_mul_f32 v[44:45], v[44:45], v[100:101]
	v_pk_mul_f32 v[40:41], v[40:41], v[104:105]
	v_pk_mul_f32 v[36:37], v[36:37], v[108:109]
	v_pk_mul_f32 v[46:47], v[46:47], v[102:103]
	v_pk_mul_f32 v[42:43], v[42:43], v[106:107]
	v_pk_mul_f32 v[38:39], v[38:39], v[110:111]
	v_pk_mul_f32 v[34:35], v[34:35], v[118:119]
	v_pk_mul_f32 v[32:33], v[32:33], v[116:117]
	v_pk_mul_f32 v[28:29], v[28:29], v[100:101]
	v_pk_mul_f32 v[24:25], v[24:25], v[104:105]
	v_pk_mul_f32 v[20:21], v[20:21], v[108:109]
	v_pk_mul_f32 v[30:31], v[30:31], v[102:103]
	v_pk_mul_f32 v[26:27], v[26:27], v[106:107]
	v_pk_mul_f32 v[22:23], v[22:23], v[110:111]
	v_pk_mul_f32 v[18:19], v[18:19], v[118:119]
	v_pk_mul_f32 v[16:17], v[16:17], v[116:117]
